# attB V gathers: scalar base (readfirstlane of the lane-0 address) + 32-bit v_mad_u32_u24 offsets and saddr-form loads instead of 64-bit per-lane addresses
# speedup vs baseline: 1.0095x; 1.0083x over previous
; __device__ __forceinline__ int crow(int r, int hi) { return (r & 3) + 8 * (r >> 2) + 4 * hi; }
; __device__ __forceinline__ float ex2(float v) { return __builtin_amdgcn_exp2f(v); }
; __device__ __forceinline__ void unit(LAS unsigned char* lds, bf16_t* P1, int b, int h, int chunk) {
;     ...
;     const float sl2 = ex2(-(float)(h + 1)) * LOG2E;
;     for (int g = 0; g < 3; ++g) {
;         const int sh = 2 * g; const float sd = sl2 * (float)(1 << sh);
;         f32x16 cb;
; #pragma unroll
;         for (int r = 0; r < 16; ++r) cb[r] = sd * (float)crow(r, hi);
;     ...
;                 { const bf16_t* vbase0 = P1 + rowbase * LDP + C_VB + g * 512 + h * 64 + r32;
.LBB0_317:
	s_andn2_b64 vcc, exec, s[30:31]
	s_cbranch_vccnz .LBB0_316
	s_lshl_b32 s50, s49, 1
	s_lshl_b32 s2, 1, s50
	s_lshr_b32 s52, 16, s50
	v_cvt_f32_u32_e32 v0, s2
	s_sub_i32 s51, 4, s50
	s_add_i32 s52, s52, 0x7ffffff
	s_lshr_b32 s53, s48, s50
	s_lshl_b32 s4, s49, 9
	s_lshl_b32 s18, s49, 10
	s_cmp_lg_u32 s49, 0
	s_cselect_b64 s[36:37], -1, 0
	s_cmp_eq_u32 s49, 2
	s_cselect_b64 s[38:39], -1, 0
	s_cmp_lg_u32 s49, 2
	v_mul_f32_e32 v122, v141, v0
	s_cselect_b64 s[2:3], -1, 0
	v_pk_mul_f32 v[14:15], v[122:123], v[86:87] op_sel_hi:[0,1]
	v_pk_mul_f32 v[12:13], v[122:123], v[88:89] op_sel_hi:[0,1]
	v_pk_mul_f32 v[10:11], v[122:123], v[90:91] op_sel_hi:[0,1]
	v_pk_mul_f32 v[8:9], v[122:123], v[92:93] op_sel_hi:[0,1]
	v_pk_mul_f32 v[6:7], v[122:123], v[94:95] op_sel_hi:[0,1]
	v_pk_mul_f32 v[4:5], v[122:123], v[96:97] op_sel_hi:[0,1]
	v_pk_mul_f32 v[2:3], v[122:123], v[98:99] op_sel_hi:[0,1]
	v_pk_mul_f32 v[0:1], v[122:123], v[100:101] op_sel_hi:[0,1]
	v_lshl_add_u64 v[124:125], v[120:121], 0, s[18:19]
	s_nop 0
	v_readfirstlane_b32 s100, v124
	v_readfirstlane_b32 s101, v125
	s_and_b64 s[40:41], s[0:1], s[2:3]
	v_add_u32_e32 v103, s53, v137
	v_add_u32_e32 v142, s53, v84
	s_lshl_b32 s18, s4, 1
	s_mov_b32 s54, s47
	s_branch .LBB0_320

; __device__ __forceinline__ void unit(LAS unsigned char* lds, bf16_t* P1, int b, int h, int chunk) {
;     ...
;                 const int ib = i0 - 128 + 32 * kb; if (ib < 0) continue;
;                 const int tk = ((ib + r32) << sh) + cls;
;                 const bf16_t* kp = P1 + (rowbase + tk) * LDP + C_KB + g * 512 + h * 64 + hi * 8;
;                 bf16x8 kfr[4];
; #pragma unroll
;                 for (int ks = 0; ks < 4; ++ks) kfr[ks] = *(const bf16x8*)(kp + ks * 16);
;                 bf16x8 vfr[4];
;                 { const bf16_t* vbase0 = P1 + rowbase * LDP + C_VB + g * 512 + h * 64 + r32;
; #pragma unroll
;                   for (int d = 0; d < 2; ++d)
; #pragma unroll
;                       for (int s = 0; s < 2; ++s)
; #pragma unroll
;                           for (int j = 0; j < 8; ++j) { const int kvl = 16 * s + 8 * (j >> 2) + 4 * hi + (j & 3); const int tok = ((ib + kvl) << sh) + cls;
;                               vfr[2 * d + s][j] = (short)vbase0[(size_t)tok * LDP + d * 32]; } }
.LBB0_323:
	s_add_i32 s5, s3, s4
	s_addk_i32 s5, 0xff80
	s_cmp_lt_i32 s5, 0
	s_cbranch_scc1 .LBB0_322
	v_add_u32_e32 v48, s4, v107
	v_lshlrev_b32_e32 v48, s50, v48
	v_add_u32_e32 v48, s2, v48
	v_ashrrev_i32_e32 v49, 31, v48
	v_lshl_add_u64 v[48:49], s[28:29], 0, v[48:49]
	v_mov_b64_e32 v[50:51], s[78:79]
	v_mad_u64_u32 v[50:51], s[42:43], v48, s33, v[50:51]
	v_mad_i32_i24 v51, v49, s33, v51
	v_lshl_add_u64 v[48:49], v[50:51], 0, s[18:19]
	s_mov_b32 s35, s19
	v_lshl_add_u64 v[48:49], v[48:49], 0, s[34:35]
	v_lshl_add_u64 v[48:49], v[48:49], 0, v[82:83]
	v_add_u32_e32 v119, s4, v109
	v_lshl_add_u64 v[50:51], v[48:49], 0, s[24:25]
	v_add_co_u32_e32 v48, vcc, s44, v48
	v_add_u32_e32 v173, 0xffffff90, v119
	s_nop 0
	v_addc_co_u32_e32 v49, vcc, 0, v49, vcc
	global_load_dwordx4 v[190:193], v[50:51], off offset:32
	global_load_dwordx4 v[194:197], v[50:51], off offset:64
	global_load_dwordx4 v[202:205], v[48:49], off offset:3072
	global_load_dwordx4 v[206:209], v[50:51], off offset:96
	v_lshlrev_b32_e32 v48, s50, v173
	v_add_u32_e32 v127, s2, v48
	v_add_u32_e32 v183, 0xffffff91, v119
	v_mad_u32_u24 v170, v127, s33, v102
	v_lshlrev_b32_e32 v127, s50, v183
	v_add_u32_e32 v127, s2, v127
	v_add_u32_e32 v184, 0xffffff92, v119
	v_mad_u32_u24 v198, v127, s33, v102
	v_lshlrev_b32_e32 v127, s50, v184
	v_add_u32_e32 v127, s2, v127
	v_add_u32_e32 v185, 0xffffff93, v119
	v_mad_u32_u24 v146, v127, s33, v102
	v_lshlrev_b32_e32 v127, s50, v185
	v_add_u32_e32 v127, s2, v127
	v_add_u32_e32 v186, 0xffffff98, v119
	v_mad_u32_u24 v210, v127, s33, v102
	v_lshlrev_b32_e32 v127, s50, v186
	v_add_u32_e32 v127, s2, v127
	v_add_u32_e32 v187, 0xffffff99, v119
	v_add_u32_e32 v174, 0xffffff80, v119
	v_mad_u32_u24 v212, v127, s33, v102
	v_lshlrev_b32_e32 v127, s50, v187
	v_lshlrev_b32_e32 v48, s50, v174
	v_add_u32_e32 v175, 0xffffff81, v119
	v_add_u32_e32 v177, 0xffffff82, v119
	v_add_u32_e32 v178, 0xffffff83, v119
	v_add_u32_e32 v179, 0xffffff88, v119
	v_add_u32_e32 v180, 0xffffff89, v119
	v_add_u32_e32 v181, 0xffffff8a, v119
	v_add_u32_e32 v182, 0xffffff8b, v119
	v_add_u32_e32 v127, s2, v127
	v_add_u32_e32 v188, 0xffffff9a, v119
	v_add_u32_e32 v189, 0xffffff9b, v119
	v_add_u32_e32 v48, s2, v48
	v_lshlrev_b32_e32 v50, s50, v175
	v_lshlrev_b32_e32 v52, s50, v177
	v_lshlrev_b32_e32 v54, s50, v178
	v_lshlrev_b32_e32 v56, s50, v179
	v_lshlrev_b32_e32 v58, s50, v180
	v_lshlrev_b32_e32 v60, s50, v181
	v_lshlrev_b32_e32 v62, s50, v182
	v_mad_u32_u24 v214, v127, s33, v102
	v_lshlrev_b32_e32 v127, s50, v188
	v_lshlrev_b32_e32 v119, s50, v189
	v_mad_u32_u24 v48, v48, s33, v102
	v_add_u32_e32 v50, s2, v50
	v_add_u32_e32 v52, s2, v52
	v_add_u32_e32 v54, s2, v54
	v_add_u32_e32 v56, s2, v56
	v_add_u32_e32 v58, s2, v58
	v_add_u32_e32 v60, s2, v60
	v_add_u32_e32 v62, s2, v62
	v_add_u32_e32 v127, s2, v127
	v_add_u32_e32 v119, s2, v119
	v_mad_u32_u24 v50, v50, s33, v102
	v_mad_u32_u24 v52, v52, s33, v102
	v_mad_u32_u24 v54, v54, s33, v102
	v_mad_u32_u24 v56, v56, s33, v102
	v_mad_u32_u24 v58, v58, s33, v102
	v_mad_u32_u24 v60, v60, s33, v102
	v_mad_u32_u24 v62, v62, s33, v102
	v_mad_u32_u24 v216, v127, s33, v102
	v_mad_u32_u24 v218, v119, s33, v102
	global_load_dword v153, v48, s[100:101]
	global_load_dword v154, v50, s[100:101]
	global_load_dword v156, v52, s[100:101]
	global_load_dword v159, v54, s[100:101]
	global_load_dword v165, v56, s[100:101]
	global_load_dword v166, v58, s[100:101]
	global_load_dword v167, v60, s[100:101]
	global_load_dword v168, v62, s[100:101]
	global_load_dword v161, v170, s[100:101]
	global_load_dword v162, v198, s[100:101]
	global_load_dword v163, v146, s[100:101]
	global_load_dword v164, v210, s[100:101]
	s_nop 0
	s_nop 0
	global_load_dword v169, v212, s[100:101]
	s_nop 0
	global_load_dword v170, v214, s[100:101]
	global_load_dword v171, v216, s[100:101]
	global_load_dword v172, v218, s[100:101]
	s_waitcnt vmcnt(17)
	v_mfma_f32_32x32x16_bf16 v[48:63], v[202:205], v[64:67], v[0:15]
	s_cmp_lg_u32 s4, 0
	v_mfma_f32_32x32x16_bf16 v[48:63], v[190:193], v[68:71], v[48:63]
	v_mfma_f32_32x32x16_bf16 v[48:63], v[194:197], v[72:75], v[48:63]
	s_waitcnt vmcnt(16)
	v_mfma_f32_32x32x16_bf16 v[48:63], v[206:209], v[76:79], v[48:63]
	s_cbranch_scc0 .LBB0_326
	s_cmpk_lg_i32 s4, 0x80
	s_cbranch_scc1 .LBB0_321
	s_branch .LBB0_327
